# P5 cq GEMM: nt policy on the A-operand (x rows) stage loads, each read by exactly one workgroup
# baseline (speedup 1.0000x reference)
.LBB0_764:
	s_or_b64 exec, exec, s[0:1]
	v_readlane_b32 s4, v254, 30
	s_movk_i32 s0, 0x400
	v_mov_b32_e32 v6, v193
	v_readlane_b32 s5, v254, 31
	s_waitcnt lgkmcnt(0)
	s_barrier
	s_andn2_b64 vcc, exec, s[4:5]
	v_readfirstlane_b32 s22, v6
	s_cbranch_vccnz .LBB0_790
	v_lshlrev_b32_e32 v3, 4, v6
	v_add_u32_e32 v0, 0x2000, v3
	v_ashrrev_i32_e32 v1, 31, v0
	v_lshrrev_b32_e32 v1, 22, v1
	v_add_u32_e32 v1, v0, v1
	v_ashrrev_i32_e32 v1, 10, v1
	v_mul_i32_i24_e32 v2, 0x400, v1
	v_sub_u32_e32 v0, v0, v2
	v_lshrrev_b32_e32 v2, 4, v0
	v_bitop3_b32 v2, v2, v0, 32 bitop3:0x6c
	v_ashrrev_i32_e32 v0, 31, v2
	v_lshrrev_b32_e32 v0, 26, v0
	v_add_u32_e32 v4, v2, v0
	v_lshlrev_b32_e32 v5, 3, v1
	v_ashrrev_i32_e32 v0, 6, v4
	v_and_b32_e32 v5, -16, v5
	v_add_u32_e32 v5, v0, v5
	v_and_b32_e32 v0, 3, v0
	s_mov_b32 s4, 0x7fffffe0
	v_lshrrev_b32_e32 v7, 2, v5
	v_lshlrev_b32_e32 v8, 1, v5
	v_and_or_b32 v0, v5, s4, v0
	v_and_b32_e32 v7, 4, v7
	v_and_b32_e32 v8, 24, v8
	v_or3_b32 v0, v0, v7, v8
	v_mul_lo_u32 v7, v0, s0
	v_lshlrev_b32_e32 v0, 5, v1
	v_and_b32_e32 v1, 0xc0, v4
	v_sub_u32_e32 v1, v2, v1
	v_ashrrev_i16_sdwa v1, v242, sext(v1) dst_sel:DWORD dst_unused:UNUSED_PAD src0_sel:DWORD src1_sel:BYTE_0
	v_and_b32_e32 v0, 32, v0
	v_bfe_i32 v1, v1, 0, 16
	v_add_u32_e32 v4, v0, v1
	v_mul_lo_u32 v2, v5, s0
	v_add_lshl_u32 v132, v7, v4, 1
	v_add_lshl_u32 v134, v4, v2, 1
	v_bfe_i32 v4, v6, 27, 1
	v_lshrrev_b32_e32 v4, 22, v4
	v_add_u32_e32 v4, v3, v4
	v_and_b32_e32 v4, 0xfffffc00, v4
	v_sub_u32_e32 v3, v3, v4
	v_lshrrev_b32_e32 v4, 4, v3
	v_ashrrev_i32_e32 v7, 31, v6
	v_bitop3_b32 v4, v4, v3, 32 bitop3:0x6c
	v_lshrrev_b32_e32 v7, 26, v7
	v_ashrrev_i32_e32 v3, 31, v4
	v_add_u32_e32 v7, v6, v7
	v_lshrrev_b32_e32 v3, 26, v3
	v_ashrrev_i32_e32 v7, 6, v7
	v_add_u32_e32 v5, v4, v3
	v_lshlrev_b32_e32 v8, 3, v7
	s_add_u32 s3, s91, 0x1300000
	v_readlane_b32 s1, v255, 45
	v_ashrrev_i32_e32 v3, 6, v5
	v_and_b32_e32 v8, -16, v8
	s_addc_u32 s6, s1, 0
	s_ashr_i32 s1, s0, 31
	v_add_u32_e32 v8, v3, v8
	v_and_b32_e32 v3, 3, v3
	s_lshl_b64 s[10:11], s[0:1], 9
	v_and_or_b32 v3, v8, s4, v3
	v_readlane_b32 s4, v255, 9
	v_readlane_b32 s15, v255, 8
	s_mul_i32 s4, s10, s4
	s_mul_hi_u32 s5, s10, s15
	s_add_i32 s14, s5, s4
	s_lshr_b64 s[4:5], s[0:1], 23
	s_mul_i32 s5, s4, s15
	v_lshrrev_b32_e32 v9, 2, v8
	v_lshlrev_b32_e32 v10, 1, v8
	s_add_i32 s14, s14, s5
	v_readlane_b32 s5, v255, 11
	v_readlane_b32 s20, v255, 10
	v_and_b32_e32 v9, 4, v9
	v_and_b32_e32 v10, 24, v10
	v_and_b32_e32 v5, 0xc0, v5
	s_mul_i32 s5, s10, s5
	s_mul_hi_u32 s16, s10, s20
	s_ashr_i32 s18, s22, 6
	v_or3_b32 v3, v3, v9, v10
	v_sub_u32_e32 v4, v4, v5
	s_add_i32 s5, s16, s5
	s_mul_i32 s4, s4, s20
	s_ashr_i32 s19, s22, 8
	s_lshl_b64 s[8:9], s[0:1], 8
	s_lshl_b32 s7, s18, 10
	v_mul_lo_u32 v9, v3, s0
	v_lshlrev_b32_e32 v3, 5, v7
	v_ashrrev_i16_sdwa v4, v242, sext(v4) dst_sel:DWORD dst_unused:UNUSED_PAD src0_sel:DWORD src1_sel:BYTE_0
	s_add_i32 s5, s5, s4
	s_mul_i32 s4, s10, s20
	v_and_b32_e32 v3, 32, v3
	v_bfe_i32 v4, v4, 0, 16
	s_add_u32 s24, s3, s4
	v_add_u32_e32 v7, v3, v4
	s_addc_u32 s25, s6, s5
	s_add_i32 s16, s7, 0
	v_add_lshl_u32 v194, v9, v7, 1
	s_add_i32 m0, s16, 0x10000
	s_mul_i32 s15, s10, s15
	global_load_lds_dwordx4 v194, s[24:25]
	s_add_i32 m0, s16, 0x12000
	s_add_u32 s4, s24, s8
	global_load_lds_dwordx4 v132, s[24:25]
	s_addc_u32 s5, s25, s9
	s_add_i32 m0, s16, 0x14000
	v_mul_lo_u32 v5, v8, s0
	global_load_lds_dwordx4 v194, s[4:5]
	s_add_i32 m0, s16, 0x16000
	s_add_u32 s28, s36, s15
	s_addc_u32 s29, s37, s14
	s_add_i32 s20, s16, 0x2000
	v_add_lshl_u32 v136, v7, v5, 1
	global_load_lds_dwordx4 v132, s[4:5]
	s_mov_b32 m0, s16
	s_add_u32 s14, s28, s8
	global_load_lds_dwordx4 v136, s[28:29] nt
	s_mov_b32 m0, s20
	s_addc_u32 s15, s29, s9
	s_add_i32 s26, s16, 0x4000
	global_load_lds_dwordx4 v134, s[28:29] nt
	s_mov_b32 m0, s26
	s_add_i32 s30, s16, 0x6000
	global_load_lds_dwordx4 v136, s[14:15] nt
	s_mov_b32 m0, s30
	s_cmp_eq_u32 s19, 1
	global_load_lds_dwordx4 v134, s[14:15] nt
	s_cselect_b64 s[14:15], -1, 0
	s_cmp_lg_u32 s19, 1
	s_cbranch_scc1 .LBB0_767
	s_barrier
.LBB0_767:
	v_bfe_u32 v147, v6, 4, 2
	s_lshr_b32 s1, s1, 26
	v_and_b32_e32 v149, 15, v6
	s_add_i32 s1, s0, s1
	v_lshlrev_b32_e32 v7, 4, v147
	v_lshlrev_b32_e32 v6, 2, v6
	s_ashr_i32 s31, s1, 6
	v_lshl_or_b32 v7, v149, 6, v7
	s_lshl_b32 s1, s19, 13
	v_and_b32_e32 v6, 32, v6
	v_bitop3_b32 v20, v7, s1, v6 bitop3:0xde
	s_lshl_b32 s1, s18, 5
	s_and_b32 s35, s1, 0x60
	v_lshl_add_u64 v[8:9], s[24:25], 0, v[194:195]
	v_mov_b32_e32 v133, v195
	s_lshl_b32 s1, s35, 7
	v_lshl_add_u64 v[10:11], s[24:25], 0, v[132:133]
	v_mov_b32_e32 v137, v195
	v_bitop3_b32 v155, v7, s1, v6 bitop3:0xde
	s_add_i32 m0, s16, 0x18000
	v_lshl_add_u64 v[6:7], v[8:9], 0, s[38:39]
	v_lshl_add_u64 v[16:17], s[28:29], 0, v[136:137]
	v_mov_b32_e32 v135, v195
	s_waitcnt vmcnt(2)
	s_barrier
	global_load_lds_dwordx4 v[6:7], off
	v_lshl_add_u64 v[6:7], v[10:11], 0, s[38:39]
	s_add_i32 m0, s16, 0x1a000
	s_add_i32 s42, s16, 0x8000
	v_lshl_add_u64 v[18:19], s[28:29], 0, v[134:135]
	global_load_lds_dwordx4 v[6:7], off
	v_lshl_add_u64 v[6:7], v[16:17], 0, s[38:39]
	s_mov_b32 m0, s42
	s_add_i32 s43, s16, 0xa000
	v_lshl_add_u64 v[12:13], s[4:5], 0, v[194:195]
	global_load_lds_dwordx4 v[6:7], off nt
	v_lshl_add_u64 v[6:7], v[18:19], 0, s[38:39]
	s_mov_b32 m0, s43
	v_lshl_add_u64 v[14:15], s[4:5], 0, v[132:133]
	global_load_lds_dwordx4 v[6:7], off nt
	s_add_i32 m0, s16, 0x1c000
	v_lshl_add_u64 v[6:7], v[12:13], 0, s[38:39]
	global_load_lds_dwordx4 v[6:7], off
	v_lshl_add_u64 v[6:7], v[14:15], 0, s[38:39]
	s_add_i32 m0, s16, 0x1e000
	s_lshl_b32 s33, s19, 6
	global_load_lds_dwordx4 v[6:7], off
	s_cmp_gt_i32 s0, 63
	s_waitcnt vmcnt(6)
	s_cselect_b64 s[18:19], -1, 0
	s_add_i32 s48, s31, -2
	v_add_u32_e32 v3, v5, v3
	v_add_u32_e32 v0, v2, v0
	s_cmpk_lt_u32 s22, 0x100
	v_add_lshl_u32 v4, v3, v4, 1
	v_mov_b32_e32 v5, v195
	v_add_lshl_u32 v0, v0, v1, 1
	v_mov_b32_e32 v1, v195
	s_cselect_b64 s[22:23], -1, 0
	v_lshl_add_u64 v[138:139], s[8:9], 0, v[4:5]
	v_lshl_add_u64 v[140:141], s[8:9], 0, v[0:1]
	s_mov_b32 s49, 0
	v_add_u32_e32 v159, 0, v20
	v_readlane_b32 s54, v255, 10
	v_readlane_b32 s55, v255, 8
	s_barrier
	s_branch .LBB0_770

.LBB0_782:
	s_add_i32 s72, s24, 2
	s_add_u32 s73, s4, 0x80
	s_addc_u32 s25, s5, 0
	s_add_i32 s88, 0, 0x10000
	s_cmp_eq_u32 s48, s24
	s_cselect_b32 s25, s69, s25
	s_cselect_b32 s24, s68, s73
	v_add_u32_e32 v146, s88, v155
	s_cselect_b32 s83, s87, s29
	s_cselect_b32 s82, s86, s28
	s_add_i32 s73, 0, 0x14000
	ds_read_b128 v[128:131], v146
	ds_read_b128 v[142:145], v146 offset:1024
	ds_read_b128 v[150:153], v146 offset:2048
	ds_read_b128 v[160:163], v146 offset:3072
	v_add_u32_e32 v146, s73, v155
	ds_read_b128 v[164:167], v146
	ds_read_b128 v[168:171], v146 offset:1024
	ds_read_b128 v[172:175], v146 offset:2048
	ds_read_b128 v[176:179], v146 offset:3072
	v_lshl_add_u64 v[156:157], s[4:5], 0, v[138:139]
	s_add_i32 m0, s16, 0xc000
	ds_read_b128 v[180:183], v159
	ds_read_b128 v[184:187], v159 offset:1024
	ds_read_b128 v[188:191], v159 offset:2048
	ds_read_b128 v[198:201], v159 offset:3072
	ds_read_b128 v[218:221], v159 offset:4096
	ds_read_b128 v[222:225], v159 offset:5120
	ds_read_b128 v[226:229], v159 offset:6144
	ds_read_b128 v[230:233], v159 offset:7168
	global_load_lds_dwordx4 v[156:157], off nt
	v_lshl_add_u64 v[156:157], s[4:5], 0, v[140:141]
	s_add_i32 m0, s16, 0xe000
	s_nop 0
	global_load_lds_dwordx4 v[156:157], off nt
	s_waitcnt vmcnt(8)
	s_waitcnt lgkmcnt(0)
	s_barrier
	s_setprio 1
	s_waitcnt lgkmcnt(0)
	v_mfma_f32_16x16x32_bf16 v[124:127], v[128:131], v[180:183], v[124:127]
	v_mfma_f32_16x16x32_bf16 v[120:123], v[150:153], v[180:183], v[120:123]
	v_mfma_f32_16x16x32_bf16 v[108:111], v[128:131], v[188:191], v[108:111]
	v_mfma_f32_16x16x32_bf16 v[104:107], v[150:153], v[188:191], v[104:107]
	v_mfma_f32_16x16x32_bf16 v[92:95], v[128:131], v[218:221], v[92:95]
	v_mfma_f32_16x16x32_bf16 v[88:91], v[150:153], v[218:221], v[88:91]
	v_mfma_f32_16x16x32_bf16 v[76:79], v[128:131], v[226:229], v[76:79]
	v_mfma_f32_16x16x32_bf16 v[72:75], v[150:153], v[226:229], v[72:75]
	v_mfma_f32_16x16x32_bf16 v[124:127], v[142:145], v[184:187], v[124:127]
	v_mfma_f32_16x16x32_bf16 v[120:123], v[160:163], v[184:187], v[120:123]
	v_mfma_f32_16x16x32_bf16 v[108:111], v[142:145], v[198:201], v[108:111]
	v_mfma_f32_16x16x32_bf16 v[104:107], v[160:163], v[198:201], v[104:107]
	v_mfma_f32_16x16x32_bf16 v[92:95], v[142:145], v[222:225], v[92:95]
	v_mfma_f32_16x16x32_bf16 v[88:91], v[160:163], v[222:225], v[88:91]
	v_mfma_f32_16x16x32_bf16 v[76:79], v[142:145], v[230:233], v[76:79]
	v_mfma_f32_16x16x32_bf16 v[72:75], v[160:163], v[230:233], v[72:75]
	s_setprio 0
	s_setprio 1
	v_mfma_f32_16x16x32_bf16 v[116:119], v[164:167], v[180:183], v[116:119]
	v_mfma_f32_16x16x32_bf16 v[112:115], v[172:175], v[180:183], v[112:115]
	v_mfma_f32_16x16x32_bf16 v[100:103], v[164:167], v[188:191], v[100:103]
	v_mfma_f32_16x16x32_bf16 v[96:99], v[172:175], v[188:191], v[96:99]
	v_mfma_f32_16x16x32_bf16 v[84:87], v[164:167], v[218:221], v[84:87]
	v_mfma_f32_16x16x32_bf16 v[80:83], v[172:175], v[218:221], v[80:83]
	v_mfma_f32_16x16x32_bf16 v[68:71], v[164:167], v[226:229], v[68:71]
	v_mfma_f32_16x16x32_bf16 v[64:67], v[172:175], v[226:229], v[64:67]
	v_mfma_f32_16x16x32_bf16 v[116:119], v[168:171], v[184:187], v[116:119]
	v_mfma_f32_16x16x32_bf16 v[112:115], v[176:179], v[184:187], v[112:115]
	v_mfma_f32_16x16x32_bf16 v[100:103], v[168:171], v[198:201], v[100:103]
	v_mfma_f32_16x16x32_bf16 v[96:99], v[176:179], v[198:201], v[96:99]
	v_mfma_f32_16x16x32_bf16 v[84:87], v[168:171], v[222:225], v[84:87]
	v_mfma_f32_16x16x32_bf16 v[80:83], v[176:179], v[222:225], v[80:83]
	v_mfma_f32_16x16x32_bf16 v[68:71], v[168:171], v[230:233], v[68:71]
	v_mfma_f32_16x16x32_bf16 v[64:67], v[176:179], v[230:233], v[64:67]
	s_setprio 0
	s_barrier
	s_add_i32 s88, s88, s7
	v_lshl_add_u64 v[156:157], s[82:83], 0, v[194:195]
	s_mov_b32 m0, s88
	ds_read_b128 v[180:183], v159 offset:16384
	ds_read_b128 v[184:187], v159 offset:17408
	ds_read_b128 v[188:191], v159 offset:18432
	ds_read_b128 v[198:201], v159 offset:19456
	ds_read_b128 v[218:221], v159 offset:20480
	ds_read_b128 v[222:225], v159 offset:21504
	ds_read_b128 v[226:229], v159 offset:22528
	ds_read_b128 v[230:233], v159 offset:23552
	global_load_lds_dwordx4 v[156:157], off
	s_add_i32 m0, s88, 0x2000
	v_lshl_add_u64 v[234:235], s[82:83], 0, v[132:133]
	s_add_u32 s82, s82, s8
	s_addc_u32 s83, s83, s9
	s_add_i32 s73, s73, s7
	global_load_lds_dwordx4 v[234:235], off
	v_lshl_add_u64 v[236:237], s[82:83], 0, v[194:195]
	s_mov_b32 m0, s73
	v_lshl_add_u64 v[238:239], s[82:83], 0, v[132:133]
	global_load_lds_dwordx4 v[236:237], off
	s_add_i32 m0, s73, 0x2000
	v_lshl_add_u64 v[240:241], s[24:25], 0, v[136:137]
	global_load_lds_dwordx4 v[238:239], off
	s_mov_b32 m0, s16
	v_lshl_add_u64 v[246:247], s[24:25], 0, v[134:135]
	global_load_lds_dwordx4 v[240:241], off nt
	s_mov_b32 m0, s20
	s_nop 0
	global_load_lds_dwordx4 v[246:247], off nt
	s_waitcnt vmcnt(8)
	s_waitcnt lgkmcnt(0)
	s_barrier
	s_setprio 1
	s_waitcnt lgkmcnt(0)
	v_mfma_f32_16x16x32_bf16 v[60:63], v[128:131], v[180:183], v[60:63]
	v_mfma_f32_16x16x32_bf16 v[56:59], v[150:153], v[180:183], v[56:59]
	v_mfma_f32_16x16x32_bf16 v[44:47], v[128:131], v[188:191], v[44:47]
	v_mfma_f32_16x16x32_bf16 v[40:43], v[150:153], v[188:191], v[40:43]
	v_mfma_f32_16x16x32_bf16 v[28:31], v[128:131], v[218:221], v[28:31]
	v_mfma_f32_16x16x32_bf16 v[24:27], v[150:153], v[218:221], v[24:27]
	v_mfma_f32_16x16x32_bf16 v[12:15], v[128:131], v[226:229], v[12:15]
	v_mfma_f32_16x16x32_bf16 v[8:11], v[150:153], v[226:229], v[8:11]
	v_mfma_f32_16x16x32_bf16 v[60:63], v[142:145], v[184:187], v[60:63]
	v_mfma_f32_16x16x32_bf16 v[56:59], v[160:163], v[184:187], v[56:59]
	v_mfma_f32_16x16x32_bf16 v[44:47], v[142:145], v[198:201], v[44:47]
	v_mfma_f32_16x16x32_bf16 v[40:43], v[160:163], v[198:201], v[40:43]
	v_mfma_f32_16x16x32_bf16 v[28:31], v[142:145], v[222:225], v[28:31]
	v_mfma_f32_16x16x32_bf16 v[24:27], v[160:163], v[222:225], v[24:27]
	v_mfma_f32_16x16x32_bf16 v[12:15], v[142:145], v[230:233], v[12:15]
	v_mfma_f32_16x16x32_bf16 v[8:11], v[160:163], v[230:233], v[8:11]
	s_setprio 0
	s_setprio 1
	v_mfma_f32_16x16x32_bf16 v[52:55], v[164:167], v[180:183], v[52:55]
	v_mfma_f32_16x16x32_bf16 v[48:51], v[172:175], v[180:183], v[48:51]
	v_mfma_f32_16x16x32_bf16 v[36:39], v[164:167], v[188:191], v[36:39]
	v_mfma_f32_16x16x32_bf16 v[32:35], v[172:175], v[188:191], v[32:35]
	v_mfma_f32_16x16x32_bf16 v[20:23], v[164:167], v[218:221], v[20:23]
	v_mfma_f32_16x16x32_bf16 v[16:19], v[172:175], v[218:221], v[16:19]
	v_mfma_f32_16x16x32_bf16 v[4:7], v[164:167], v[226:229], v[4:7]
	v_mfma_f32_16x16x32_bf16 v[0:3], v[172:175], v[226:229], v[0:3]
	v_mfma_f32_16x16x32_bf16 v[52:55], v[168:171], v[184:187], v[52:55]
	v_mfma_f32_16x16x32_bf16 v[48:51], v[176:179], v[184:187], v[48:51]
	v_mfma_f32_16x16x32_bf16 v[36:39], v[168:171], v[198:201], v[36:39]
	v_mfma_f32_16x16x32_bf16 v[32:35], v[176:179], v[198:201], v[32:35]
	v_mfma_f32_16x16x32_bf16 v[20:23], v[168:171], v[222:225], v[20:23]
	v_mfma_f32_16x16x32_bf16 v[16:19], v[176:179], v[222:225], v[16:19]
	v_mfma_f32_16x16x32_bf16 v[4:7], v[168:171], v[230:233], v[4:7]
	v_mfma_f32_16x16x32_bf16 v[0:3], v[176:179], v[230:233], v[0:3]
	s_setprio 0
	s_barrier
	s_add_i32 s73, 0, 0x18000
	v_add_u32_e32 v146, s73, v155
	s_add_i32 s82, 0, 0x1c000
	ds_read_b128 v[128:131], v146
	ds_read_b128 v[142:145], v146 offset:1024
	ds_read_b128 v[150:153], v146 offset:2048
	ds_read_b128 v[160:163], v146 offset:3072
	v_add_u32_e32 v146, s82, v155
	ds_read_b128 v[164:167], v146
	ds_read_b128 v[168:171], v146 offset:1024
	ds_read_b128 v[172:175], v146 offset:2048
	ds_read_b128 v[176:179], v146 offset:3072
	s_add_u32 s24, s24, s8
	s_addc_u32 s25, s25, s9
	s_mov_b32 m0, s26
	v_lshl_add_u64 v[248:249], s[24:25], 0, v[136:137]
	ds_read_b128 v[180:183], v159 offset:32768
	ds_read_b128 v[184:187], v159 offset:33792
	ds_read_b128 v[188:191], v159 offset:34816
	ds_read_b128 v[198:201], v159 offset:35840
	ds_read_b128 v[218:221], v159 offset:36864
	ds_read_b128 v[222:225], v159 offset:37888
	ds_read_b128 v[226:229], v159 offset:38912
	ds_read_b128 v[230:233], v159 offset:39936
	global_load_lds_dwordx4 v[248:249], off nt
	v_lshl_add_u64 v[248:249], s[24:25], 0, v[134:135]
	s_mov_b32 m0, s30
	s_nop 0
	global_load_lds_dwordx4 v[248:249], off nt
	s_waitcnt vmcnt(8)
	s_waitcnt lgkmcnt(0)
	s_barrier
	s_setprio 1
	s_waitcnt lgkmcnt(0)
	v_mfma_f32_16x16x32_bf16 v[124:127], v[128:131], v[180:183], v[124:127]
	v_mfma_f32_16x16x32_bf16 v[120:123], v[150:153], v[180:183], v[120:123]
	v_mfma_f32_16x16x32_bf16 v[108:111], v[128:131], v[188:191], v[108:111]
	v_mfma_f32_16x16x32_bf16 v[104:107], v[150:153], v[188:191], v[104:107]
	v_mfma_f32_16x16x32_bf16 v[92:95], v[128:131], v[218:221], v[92:95]
	v_mfma_f32_16x16x32_bf16 v[88:91], v[150:153], v[218:221], v[88:91]
	v_mfma_f32_16x16x32_bf16 v[76:79], v[128:131], v[226:229], v[76:79]
	v_mfma_f32_16x16x32_bf16 v[72:75], v[150:153], v[226:229], v[72:75]
	v_mfma_f32_16x16x32_bf16 v[124:127], v[142:145], v[184:187], v[124:127]
	v_mfma_f32_16x16x32_bf16 v[120:123], v[160:163], v[184:187], v[120:123]
	v_mfma_f32_16x16x32_bf16 v[108:111], v[142:145], v[198:201], v[108:111]
	v_mfma_f32_16x16x32_bf16 v[104:107], v[160:163], v[198:201], v[104:107]
	v_mfma_f32_16x16x32_bf16 v[92:95], v[142:145], v[222:225], v[92:95]
	v_mfma_f32_16x16x32_bf16 v[88:91], v[160:163], v[222:225], v[88:91]
	v_mfma_f32_16x16x32_bf16 v[76:79], v[142:145], v[230:233], v[76:79]
	v_mfma_f32_16x16x32_bf16 v[72:75], v[160:163], v[230:233], v[72:75]
	s_setprio 0
	s_setprio 1
	v_mfma_f32_16x16x32_bf16 v[116:119], v[164:167], v[180:183], v[116:119]
	v_mfma_f32_16x16x32_bf16 v[112:115], v[172:175], v[180:183], v[112:115]
	v_mfma_f32_16x16x32_bf16 v[100:103], v[164:167], v[188:191], v[100:103]
	v_mfma_f32_16x16x32_bf16 v[96:99], v[172:175], v[188:191], v[96:99]
	v_mfma_f32_16x16x32_bf16 v[84:87], v[164:167], v[218:221], v[84:87]
	v_mfma_f32_16x16x32_bf16 v[80:83], v[172:175], v[218:221], v[80:83]
	v_mfma_f32_16x16x32_bf16 v[68:71], v[164:167], v[226:229], v[68:71]
	v_mfma_f32_16x16x32_bf16 v[64:67], v[172:175], v[226:229], v[64:67]
	v_mfma_f32_16x16x32_bf16 v[116:119], v[168:171], v[184:187], v[116:119]
	v_mfma_f32_16x16x32_bf16 v[112:115], v[176:179], v[184:187], v[112:115]
	v_mfma_f32_16x16x32_bf16 v[100:103], v[168:171], v[198:201], v[100:103]
	v_mfma_f32_16x16x32_bf16 v[96:99], v[176:179], v[198:201], v[96:99]
	v_mfma_f32_16x16x32_bf16 v[84:87], v[168:171], v[222:225], v[84:87]
	v_mfma_f32_16x16x32_bf16 v[80:83], v[176:179], v[222:225], v[80:83]
	v_mfma_f32_16x16x32_bf16 v[68:71], v[168:171], v[230:233], v[68:71]
	v_mfma_f32_16x16x32_bf16 v[64:67], v[176:179], v[230:233], v[64:67]
	s_setprio 0
	s_barrier
	s_add_i32 s24, s73, s7
	v_lshl_add_u64 v[156:157], v[156:157], 0, s[38:39]
	s_mov_b32 m0, s24
	ds_read_b128 v[180:183], v159 offset:49152
	ds_read_b128 v[184:187], v159 offset:50176
	ds_read_b128 v[188:191], v159 offset:51200
	ds_read_b128 v[198:201], v159 offset:52224
	ds_read_b128 v[218:221], v159 offset:53248
	ds_read_b128 v[222:225], v159 offset:54272
	ds_read_b128 v[226:229], v159 offset:55296
	ds_read_b128 v[230:233], v159 offset:56320
	global_load_lds_dwordx4 v[156:157], off
	v_lshl_add_u64 v[156:157], v[234:235], 0, s[38:39]
	s_add_i32 m0, s24, 0x2000
	s_add_i32 s24, s82, s7
	global_load_lds_dwordx4 v[156:157], off
	v_lshl_add_u64 v[156:157], v[236:237], 0, s[38:39]
	s_mov_b32 m0, s24
	s_nop 0
	global_load_lds_dwordx4 v[156:157], off
	v_lshl_add_u64 v[156:157], v[238:239], 0, s[38:39]
	s_add_i32 m0, s24, 0x2000
	s_nop 0
	global_load_lds_dwordx4 v[156:157], off
	v_lshl_add_u64 v[156:157], v[240:241], 0, s[38:39]
	s_mov_b32 m0, s42
	s_nop 0
	global_load_lds_dwordx4 v[156:157], off nt
	v_lshl_add_u64 v[156:157], v[246:247], 0, s[38:39]
	s_mov_b32 m0, s43
	s_nop 0
	global_load_lds_dwordx4 v[156:157], off nt
	s_waitcnt vmcnt(8)
	s_waitcnt lgkmcnt(0)
	s_barrier
	s_setprio 1
	s_waitcnt lgkmcnt(0)
	v_mfma_f32_16x16x32_bf16 v[60:63], v[128:131], v[180:183], v[60:63]
	v_mfma_f32_16x16x32_bf16 v[56:59], v[150:153], v[180:183], v[56:59]
	v_mfma_f32_16x16x32_bf16 v[44:47], v[128:131], v[188:191], v[44:47]
	v_mfma_f32_16x16x32_bf16 v[40:43], v[150:153], v[188:191], v[40:43]
	v_mfma_f32_16x16x32_bf16 v[28:31], v[128:131], v[218:221], v[28:31]
	v_mfma_f32_16x16x32_bf16 v[24:27], v[150:153], v[218:221], v[24:27]
	v_mfma_f32_16x16x32_bf16 v[12:15], v[128:131], v[226:229], v[12:15]
	v_mfma_f32_16x16x32_bf16 v[8:11], v[150:153], v[226:229], v[8:11]
	v_mfma_f32_16x16x32_bf16 v[60:63], v[142:145], v[184:187], v[60:63]
	v_mfma_f32_16x16x32_bf16 v[56:59], v[160:163], v[184:187], v[56:59]
	v_mfma_f32_16x16x32_bf16 v[44:47], v[142:145], v[198:201], v[44:47]
	v_mfma_f32_16x16x32_bf16 v[40:43], v[160:163], v[198:201], v[40:43]
	v_mfma_f32_16x16x32_bf16 v[28:31], v[142:145], v[222:225], v[28:31]
	v_mfma_f32_16x16x32_bf16 v[24:27], v[160:163], v[222:225], v[24:27]
	v_mfma_f32_16x16x32_bf16 v[12:15], v[142:145], v[230:233], v[12:15]
	v_mfma_f32_16x16x32_bf16 v[8:11], v[160:163], v[230:233], v[8:11]
	s_setprio 0
	s_setprio 1
	v_mfma_f32_16x16x32_bf16 v[52:55], v[164:167], v[180:183], v[52:55]
	v_mfma_f32_16x16x32_bf16 v[48:51], v[172:175], v[180:183], v[48:51]
	v_mfma_f32_16x16x32_bf16 v[36:39], v[164:167], v[188:191], v[36:39]
	v_mfma_f32_16x16x32_bf16 v[32:35], v[172:175], v[188:191], v[32:35]
	v_mfma_f32_16x16x32_bf16 v[20:23], v[164:167], v[218:221], v[20:23]
	v_mfma_f32_16x16x32_bf16 v[16:19], v[172:175], v[218:221], v[16:19]
	v_mfma_f32_16x16x32_bf16 v[4:7], v[164:167], v[226:229], v[4:7]
	v_mfma_f32_16x16x32_bf16 v[0:3], v[172:175], v[226:229], v[0:3]
	v_mfma_f32_16x16x32_bf16 v[52:55], v[168:171], v[184:187], v[52:55]
	v_mfma_f32_16x16x32_bf16 v[48:51], v[176:179], v[184:187], v[48:51]
	v_mfma_f32_16x16x32_bf16 v[36:39], v[168:171], v[198:201], v[36:39]
	v_mfma_f32_16x16x32_bf16 v[32:35], v[176:179], v[198:201], v[32:35]
	v_mfma_f32_16x16x32_bf16 v[20:23], v[168:171], v[222:225], v[20:23]
	v_mfma_f32_16x16x32_bf16 v[16:19], v[176:179], v[222:225], v[16:19]
	v_mfma_f32_16x16x32_bf16 v[4:7], v[168:171], v[230:233], v[4:7]
	v_mfma_f32_16x16x32_bf16 v[0:3], v[176:179], v[230:233], v[0:3]
	s_setprio 0
	s_barrier
	s_add_u32 s4, s4, 0x100
	s_addc_u32 s5, s5, 0
	s_add_u32 s28, s28, 0x100
	s_addc_u32 s29, s29, 0
	s_cmp_ge_i32 s72, s31
	s_mov_b32 s24, s72
	s_cbranch_scc0 .LBB0_782
	s_movk_i32 s83, 0x7f
